# attention tile loop: early exit of the rescale decision chain when no row maximum grew past the threshold (alpha = 1 set directly)
# speedup vs baseline: 1.0014x; 1.0014x over previous
; __device__ __forceinline__ void partialSM(f32x16& p0, f32x16& p1, float& m_reg, float& mn, float& alpha, int rem, int hi) {
;     ...
;   float pmax = p0[0];
; #pragma unroll
;   for (int r = 1; r < 16; ++r) pmax = fmaxf(pmax, p0[r]);
; #pragma unroll
;   for (int r = 0; r < 16; ++r) pmax = fmaxf(pmax, p1[r]);
;   { auto rr = __builtin_amdgcn_permlane32_swap(__float_as_uint(pmax), __float_as_uint(pmax), false, false);
;     pmax = fmaxf(__uint_as_float(rr[0]), __uint_as_float(rr[1])); }
;   if (__builtin_expect(__all(pmax - m_reg <= THR / SCALE), 1)) { mn = m_reg; alpha = 1.f; }
;   else { mn = fmaxf(m_reg, pmax); alpha = __builtin_amdgcn_exp2f((m_reg - mn) * C); m_reg = mn; }
; __device__ __forceinline__ void dattn_unit(const bf16* __restrict__ Qb, const bf16* __restrict__ Kh, const bf16* __restrict__ Vh, int nq, int kv_lo, int kv_hi, int NT, ...
;     ...
;       if (__any(al < 1.f)) { if (hi == 0) al_l[r32] = al; asm volatile("s_waitcnt lgkmcnt(0)" ::: "memory");
.LBB0_946:
	s_nop 7
	v_max_f32_e32 v0, v147, v147
	v_max_f32_e32 v194, v146, v146
	v_max_f32_e32 v0, v194, v0
	v_max3_f32 v0, v0, v148, v149
	v_max3_f32 v0, v0, v150, v151
	v_max3_f32 v0, v0, v152, v153
	v_max3_f32 v0, v0, v154, v155
	v_max3_f32 v0, v0, v156, v157
	v_max3_f32 v0, v0, v158, v159
	v_max3_f32 v0, v0, v160, v161
	v_max3_f32 v0, v0, v130, v131
	v_max3_f32 v0, v0, v132, v133
	v_max3_f32 v0, v0, v134, v135
	v_max3_f32 v0, v0, v136, v137
	v_max3_f32 v0, v0, v138, v139
	v_max3_f32 v0, v0, v140, v141
	v_max3_f32 v0, v0, v142, v143
	v_max3_f32 v0, v0, v144, v145
	v_mov_b32_e32 v194, v0
	s_nop 1
	v_permlane32_swap_b32_e32 v0, v194
	v_max_f32_e32 v194, v194, v194
	v_max_f32_e32 v0, v0, v0
	v_max_f32_e32 v0, v0, v194
	v_sub_f32_e32 v194, v0, v246
	s_mov_b32 s4, 0x42b504f3
	v_cmp_ge_f32_e32 vcc, s4, v194
	s_cmp_eq_u64 vcc, exec
	s_cbranch_scc0 .Latt_slowchain
	s_mov_b64 s[4:5], -1
	v_mov_b32_e32 v0, 1.0
	s_branch .LBB0_937
.Latt_slowchain:
	s_mov_b64 s[4:5], 0
	v_max_f32_e32 v194, v246, v246
	v_max_f32_e32 v248, v194, v0
	v_sub_f32_e32 v0, v246, v248
	v_mul_f32_e32 v0, 0x3e0293ee, v0
	v_exp_f32_e32 v0, v0
	s_nop 0
	v_cmp_gt_f32_e32 vcc, 1.0, v0
	s_cbranch_vccz .LBB0_937
	s_and_saveexec_b64 s[6:7], s[0:1]
	s_cbranch_execz .LBB0_936
	ds_write_b32 v234, v0 offset:128
	s_branch .LBB0_936
